# conv loop rewritten: all 13 loads of an item issued together (boundary taps exec-masked into zeroed registers), one wait per item instead of four
# speedup vs baseline: 1.0020x; 1.0020x over previous
; __device__ __forceinline__ unsigned cvt_pk_bf16(float lo, float hi) { f32x2_t v = {lo, hi}; bf16x2_t b = __builtin_convertvector(v, bf16x2_t); return __builtin_bit_cast(unsigned, b); }
; __device__ __forceinline__ void conv_phase(bf16_t* proj, const float* cw, int G) {
;     int tid_ = threadIdx.x; asm volatile("" : "+v"(tid_));
;     for (int item = blockIdx.x * 512 + tid_; item < M * 48; item += G * 512) {
;         const int row = item / 48, ch = (item % 48) * 8, t = row % SEQ;
;         const bf16_t* pr = proj + (size_t)row * NIN;
;         float accv[8];
; #pragma unroll
;         for (int i = 0; i < 8; ++i) accv[i] = 0.f;
; #pragma unroll
;         for (int k = 0; k < 3; ++k) {
;             const int tt = t + k - 1;
;             if (tt < 0 || tt >= SEQ) continue;
;             const bf16_t* p2 = pr + (ptrdiff_t)(k - 1) * NIN;
;             const u32x4 uu = *(const u32x4*)(p2 + PC_U + ch), cc = *(const u32x4*)(p2 + PC_CG + ch);
;             const f32x4 w0 = *(const f32x4*)(cw + k * 384 + ch), w1 = *(const f32x4*)(cw + k * 384 + ch + 4);
; #pragma unroll
;             for (int i = 0; i < 4; ++i) {
;                 const float ulo = __uint_as_float(uu[i] << 16), uhi = __uint_as_float(uu[i] & 0xffff0000u);
;                 const float clo = __uint_as_float(cc[i] << 16), chi = __uint_as_float(cc[i] & 0xffff0000u);
;                 const float wlo = (i < 2) ? w0[2 * i] : w1[2 * i - 4], whi = (i < 2) ? w0[2 * i + 1] : w1[2 * i - 3];
;                 accv[2 * i] += wlo * ulo * clo; accv[2 * i + 1] += whi * uhi * chi;
;             }
;         }
;         const u32x4 bb = *(const u32x4*)(pr + PC_BG + ch);
;         u32x4 o;
; #pragma unroll
;         for (int i = 0; i < 4; ++i) { const float blo = __uint_as_float(bb[i] << 16), bhi = __uint_as_float(bb[i] & 0xffff0000u); o[i] = cvt_pk_bf16(blo * accv[2 * i], bhi * accv[2 * i + 1]); }
;         *(u32x4*)(proj + (size_t)row * NIN + PC_BG + ch) = o;
;     }
; }
.Lcv0_go:
	s_mov_b32 s2, s93
	v_add_u32_e32 v1, s95, v0
	v_cmp_gt_i32_e32 vcc, s2, v1
	s_and_saveexec_b64 s[2:3], vcc
	s_cbranch_execz .LBB0_570
	s_movk_i32 s92, 0xfe80
	s_movk_i32 s96, 0xbfff
	s_mov_b32 s97, 0x2aaaaaab
	s_movk_i32 s15, 0x1800
	v_mov_b64_e32 v[2:3], s[48:49]
.Lcf0_loop:
	v_add_u32_e32 v1, s95, v154
	v_lshlrev_b32_e32 v0, 3, v1
	v_mul_hi_i32 v4, v1, s97
	v_lshrrev_b32_e32 v5, 31, v4
	v_ashrrev_i32_e32 v4, 3, v4
	v_add_u32_e32 v6, v4, v5
	v_mad_u64_u32 v[4:5], s[98:99], v6, s92, v[0:1]
	v_and_b32_e32 v18, 0x3fff, v6
	v_ashrrev_i32_e32 v5, 31, v4
	v_mad_i64_i32 v[6:7], s[98:99], v6, s15, v[2:3]
	v_lshl_add_u64 v[12:13], v[4:5], 2, s[46:47]
	v_lshl_add_u64 v[4:5], v[4:5], 1, v[6:7]
	v_mov_b64_e32 v[56:57], 0
	v_mov_b64_e32 v[58:59], 0
	v_mov_b64_e32 v[60:61], 0
	v_mov_b64_e32 v[62:63], 0
	v_mov_b64_e32 v[72:73], 0
	v_mov_b64_e32 v[74:75], 0
	v_mov_b64_e32 v[76:77], 0
	v_mov_b64_e32 v[78:79], 0
	v_mov_b64_e32 v[20:21], 0
	v_mov_b64_e32 v[22:23], 0
	v_mov_b64_e32 v[24:25], 0
	v_mov_b64_e32 v[26:27], 0
	global_load_dwordx4 v[64:67], v[4:5], off offset:2048
	global_load_dwordx4 v[68:71], v[4:5], off offset:2816
	global_load_dwordx4 v[108:111], v[4:5], off
	global_load_dwordx4 v[80:83], v[12:13], off
	global_load_dwordx4 v[84:87], v[12:13], off offset:16
	global_load_dwordx4 v[88:91], v[12:13], off offset:1536
	global_load_dwordx4 v[92:95], v[12:13], off offset:1552
	global_load_dwordx4 v[100:103], v[12:13], off offset:3072
	global_load_dwordx4 v[104:107], v[12:13], off offset:3088
	v_add_u32_e32 v8, 0xffffbfff, v18
	v_cmp_lt_u32_e32 vcc, s96, v8
	s_and_saveexec_b64 s[98:99], vcc
	v_add_co_u32_e32 v30, vcc, 0xfffff000, v4
	s_nop 1
	v_addc_co_u32_e32 v31, vcc, -1, v5, vcc
	global_load_dwordx4 v[56:59], v[30:31], off
	global_load_dwordx4 v[60:63], v[30:31], off offset:768
	s_mov_b64 exec, s[98:99]
	v_add_u32_e32 v8, 0xffffc001, v18
	v_cmp_lt_u32_e32 vcc, s96, v8
	s_and_saveexec_b64 s[98:99], vcc
	v_add_co_u32_e32 v32, vcc, 0x2000, v4
	s_nop 1
	v_addc_co_u32_e32 v33, vcc, 0, v5, vcc
	global_load_dwordx4 v[72:75], v[32:33], off
	global_load_dwordx4 v[76:79], v[32:33], off offset:768
	s_mov_b64 exec, s[98:99]
	s_waitcnt vmcnt(0)
	v_lshlrev_b32_e32 v112, 16, v56
	v_and_b32_e32 v113, 0xffff0000, v56
	v_lshlrev_b32_e32 v114, 16, v57
	v_and_b32_e32 v115, 0xffff0000, v57
	v_lshlrev_b32_e32 v116, 16, v58
	v_and_b32_e32 v117, 0xffff0000, v58
	v_lshlrev_b32_e32 v118, 16, v59
	v_and_b32_e32 v119, 0xffff0000, v59
	v_pk_mul_f32 v[112:113], v[80:81], v[112:113]
	v_pk_mul_f32 v[114:115], v[82:83], v[114:115]
	v_pk_mul_f32 v[116:117], v[84:85], v[116:117]
	v_pk_mul_f32 v[118:119], v[86:87], v[118:119]
	v_lshlrev_b32_e32 v120, 16, v60
	v_and_b32_e32 v121, 0xffff0000, v60
	v_lshlrev_b32_e32 v122, 16, v61
	v_and_b32_e32 v123, 0xffff0000, v61
	v_lshlrev_b32_e32 v124, 16, v62
	v_and_b32_e32 v125, 0xffff0000, v62
	v_lshlrev_b32_e32 v126, 16, v63
	v_and_b32_e32 v127, 0xffff0000, v63
	v_pk_fma_f32 v[20:21], v[112:113], v[120:121], v[20:21]
	v_pk_fma_f32 v[22:23], v[114:115], v[122:123], v[22:23]
	v_pk_fma_f32 v[24:25], v[116:117], v[124:125], v[24:25]
	v_pk_fma_f32 v[26:27], v[118:119], v[126:127], v[26:27]
	v_lshlrev_b32_e32 v112, 16, v64
	v_and_b32_e32 v113, 0xffff0000, v64
	v_lshlrev_b32_e32 v114, 16, v65
	v_and_b32_e32 v115, 0xffff0000, v65
	v_lshlrev_b32_e32 v116, 16, v66
	v_and_b32_e32 v117, 0xffff0000, v66
	v_lshlrev_b32_e32 v118, 16, v67
	v_and_b32_e32 v119, 0xffff0000, v67
	v_pk_mul_f32 v[112:113], v[88:89], v[112:113]
	v_pk_mul_f32 v[114:115], v[90:91], v[114:115]
	v_pk_mul_f32 v[116:117], v[92:93], v[116:117]
	v_pk_mul_f32 v[118:119], v[94:95], v[118:119]
	v_lshlrev_b32_e32 v120, 16, v68
	v_and_b32_e32 v121, 0xffff0000, v68
	v_lshlrev_b32_e32 v122, 16, v69
	v_and_b32_e32 v123, 0xffff0000, v69
	v_lshlrev_b32_e32 v124, 16, v70
	v_and_b32_e32 v125, 0xffff0000, v70
	v_lshlrev_b32_e32 v126, 16, v71
	v_and_b32_e32 v127, 0xffff0000, v71
	v_pk_fma_f32 v[20:21], v[112:113], v[120:121], v[20:21]
	v_pk_fma_f32 v[22:23], v[114:115], v[122:123], v[22:23]
	v_pk_fma_f32 v[24:25], v[116:117], v[124:125], v[24:25]
	v_pk_fma_f32 v[26:27], v[118:119], v[126:127], v[26:27]
	v_lshlrev_b32_e32 v112, 16, v72
	v_and_b32_e32 v113, 0xffff0000, v72
	v_lshlrev_b32_e32 v114, 16, v73
	v_and_b32_e32 v115, 0xffff0000, v73
	v_lshlrev_b32_e32 v116, 16, v74
	v_and_b32_e32 v117, 0xffff0000, v74
	v_lshlrev_b32_e32 v118, 16, v75
	v_and_b32_e32 v119, 0xffff0000, v75
	v_pk_mul_f32 v[112:113], v[100:101], v[112:113]
	v_pk_mul_f32 v[114:115], v[102:103], v[114:115]
	v_pk_mul_f32 v[116:117], v[104:105], v[116:117]
	v_pk_mul_f32 v[118:119], v[106:107], v[118:119]
	v_lshlrev_b32_e32 v120, 16, v76
	v_and_b32_e32 v121, 0xffff0000, v76
	v_lshlrev_b32_e32 v122, 16, v77
	v_and_b32_e32 v123, 0xffff0000, v77
	v_lshlrev_b32_e32 v124, 16, v78
	v_and_b32_e32 v125, 0xffff0000, v78
	v_lshlrev_b32_e32 v126, 16, v79
	v_and_b32_e32 v127, 0xffff0000, v79
	v_pk_fma_f32 v[20:21], v[112:113], v[120:121], v[20:21]
	v_pk_fma_f32 v[22:23], v[114:115], v[122:123], v[22:23]
	v_pk_fma_f32 v[24:25], v[116:117], v[124:125], v[24:25]
	v_pk_fma_f32 v[26:27], v[118:119], v[126:127], v[26:27]
	v_lshlrev_b32_e32 v112, 16, v108
	v_and_b32_e32 v113, 0xffff0000, v108
	v_lshlrev_b32_e32 v114, 16, v109
	v_and_b32_e32 v115, 0xffff0000, v109
	v_lshlrev_b32_e32 v116, 16, v110
	v_and_b32_e32 v117, 0xffff0000, v110
	v_lshlrev_b32_e32 v118, 16, v111
	v_and_b32_e32 v119, 0xffff0000, v111
	v_pk_mul_f32 v[20:21], v[20:21], v[112:113]
	v_pk_mul_f32 v[22:23], v[22:23], v[114:115]
	v_pk_mul_f32 v[24:25], v[24:25], v[116:117]
	v_pk_mul_f32 v[26:27], v[26:27], v[118:119]
	v_cvt_pk_bf16_f32 v112, v20, v21
	v_cvt_pk_bf16_f32 v113, v22, v23
	v_cvt_pk_bf16_f32 v114, v24, v25
	v_cvt_pk_bf16_f32 v115, v26, v27
	global_store_dwordx4 v[4:5], v[112:115], off
	s_add_i32 s95, s95, s94
	s_cmp_lt_i32 s95, s93
	s_cbranch_scc1 .Lcf0_loop

; __device__ __forceinline__ unsigned cvt_pk_bf16(float lo, float hi) { f32x2_t v = {lo, hi}; bf16x2_t b = __builtin_convertvector(v, bf16x2_t); return __builtin_bit_cast(unsigned, b); }
; __device__ __forceinline__ void conv_phase(bf16_t* proj, const float* cw, int G) {
;     int tid_ = threadIdx.x; asm volatile("" : "+v"(tid_));
;     for (int item = blockIdx.x * 512 + tid_; item < M * 48; item += G * 512) {
;         const int row = item / 48, ch = (item % 48) * 8, t = row % SEQ;
;         const bf16_t* pr = proj + (size_t)row * NIN;
;         float accv[8];
; #pragma unroll
;         for (int i = 0; i < 8; ++i) accv[i] = 0.f;
; #pragma unroll
;         for (int k = 0; k < 3; ++k) {
;             const int tt = t + k - 1;
;             if (tt < 0 || tt >= SEQ) continue;
;             const bf16_t* p2 = pr + (ptrdiff_t)(k - 1) * NIN;
;             const u32x4 uu = *(const u32x4*)(p2 + PC_U + ch), cc = *(const u32x4*)(p2 + PC_CG + ch);
;             const f32x4 w0 = *(const f32x4*)(cw + k * 384 + ch), w1 = *(const f32x4*)(cw + k * 384 + ch + 4);
; #pragma unroll
;             for (int i = 0; i < 4; ++i) {
;                 const float ulo = __uint_as_float(uu[i] << 16), uhi = __uint_as_float(uu[i] & 0xffff0000u);
;                 const float clo = __uint_as_float(cc[i] << 16), chi = __uint_as_float(cc[i] & 0xffff0000u);
;                 const float wlo = (i < 2) ? w0[2 * i] : w1[2 * i - 4], whi = (i < 2) ? w0[2 * i + 1] : w1[2 * i - 3];
;                 accv[2 * i] += wlo * ulo * clo; accv[2 * i + 1] += whi * uhi * chi;
;             }
;         }
;         const u32x4 bb = *(const u32x4*)(pr + PC_BG + ch);
;         u32x4 o;
; #pragma unroll
;         for (int i = 0; i < 4; ++i) { const float blo = __uint_as_float(bb[i] << 16), bhi = __uint_as_float(bb[i] & 0xffff0000u); o[i] = cvt_pk_bf16(blo * accv[2 * i], bhi * accv[2 * i + 1]); }
;         *(u32x4*)(proj + (size_t)row * NIN + PC_BG + ch) = o;
;     }
; }
.Lcv1_go:
	s_mov_b32 s4, s93
	v_add_u32_e32 v1, s95, v0
	v_cmp_gt_i32_e32 vcc, s4, v1
	s_and_saveexec_b64 s[4:5], vcc
	s_cbranch_execz .LBB0_1282
	s_add_u32 s8, s40, 0xc1200
	s_addc_u32 s9, s41, 0
	s_movk_i32 s92, 0xfe80
	s_movk_i32 s96, 0xbfff
	s_mov_b32 s97, 0x2aaaaaab
	s_movk_i32 s15, 0x1800
	v_mov_b64_e32 v[2:3], s[44:45]
.Lcf1_loop:
	v_add_u32_e32 v1, s95, v154
	v_lshlrev_b32_e32 v0, 3, v1
	v_mul_hi_i32 v4, v1, s97
	v_lshrrev_b32_e32 v5, 31, v4
	v_ashrrev_i32_e32 v4, 3, v4
	v_add_u32_e32 v6, v4, v5
	v_mad_u64_u32 v[4:5], s[98:99], v6, s92, v[0:1]
	v_and_b32_e32 v18, 0x3fff, v6
	v_ashrrev_i32_e32 v5, 31, v4
	v_mad_i64_i32 v[6:7], s[98:99], v6, s15, v[2:3]
	v_lshl_add_u64 v[12:13], v[4:5], 2, s[8:9]
	v_lshl_add_u64 v[4:5], v[4:5], 1, v[6:7]
	v_mov_b64_e32 v[56:57], 0
	v_mov_b64_e32 v[58:59], 0
	v_mov_b64_e32 v[60:61], 0
	v_mov_b64_e32 v[62:63], 0
	v_mov_b64_e32 v[72:73], 0
	v_mov_b64_e32 v[74:75], 0
	v_mov_b64_e32 v[76:77], 0
	v_mov_b64_e32 v[78:79], 0
	v_mov_b64_e32 v[20:21], 0
	v_mov_b64_e32 v[22:23], 0
	v_mov_b64_e32 v[24:25], 0
	v_mov_b64_e32 v[26:27], 0
	global_load_dwordx4 v[64:67], v[4:5], off offset:2048
	global_load_dwordx4 v[68:71], v[4:5], off offset:2816
	global_load_dwordx4 v[108:111], v[4:5], off
	global_load_dwordx4 v[80:83], v[12:13], off
	global_load_dwordx4 v[84:87], v[12:13], off offset:16
	global_load_dwordx4 v[88:91], v[12:13], off offset:1536
	global_load_dwordx4 v[92:95], v[12:13], off offset:1552
	global_load_dwordx4 v[100:103], v[12:13], off offset:3072
	global_load_dwordx4 v[104:107], v[12:13], off offset:3088
	v_add_u32_e32 v8, 0xffffbfff, v18
	v_cmp_lt_u32_e32 vcc, s96, v8
	s_and_saveexec_b64 s[98:99], vcc
	v_add_co_u32_e32 v30, vcc, 0xfffff000, v4
	s_nop 1
	v_addc_co_u32_e32 v31, vcc, -1, v5, vcc
	global_load_dwordx4 v[56:59], v[30:31], off
	global_load_dwordx4 v[60:63], v[30:31], off offset:768
	s_mov_b64 exec, s[98:99]
	v_add_u32_e32 v8, 0xffffc001, v18
	v_cmp_lt_u32_e32 vcc, s96, v8
	s_and_saveexec_b64 s[98:99], vcc
	v_add_co_u32_e32 v32, vcc, 0x2000, v4
	s_nop 1
	v_addc_co_u32_e32 v33, vcc, 0, v5, vcc
	global_load_dwordx4 v[72:75], v[32:33], off
	global_load_dwordx4 v[76:79], v[32:33], off offset:768
	s_mov_b64 exec, s[98:99]
	s_waitcnt vmcnt(0)
	v_lshlrev_b32_e32 v112, 16, v56
	v_and_b32_e32 v113, 0xffff0000, v56
	v_lshlrev_b32_e32 v114, 16, v57
	v_and_b32_e32 v115, 0xffff0000, v57
	v_lshlrev_b32_e32 v116, 16, v58
	v_and_b32_e32 v117, 0xffff0000, v58
	v_lshlrev_b32_e32 v118, 16, v59
	v_and_b32_e32 v119, 0xffff0000, v59
	v_pk_mul_f32 v[112:113], v[80:81], v[112:113]
	v_pk_mul_f32 v[114:115], v[82:83], v[114:115]
	v_pk_mul_f32 v[116:117], v[84:85], v[116:117]
	v_pk_mul_f32 v[118:119], v[86:87], v[118:119]
	v_lshlrev_b32_e32 v120, 16, v60
	v_and_b32_e32 v121, 0xffff0000, v60
	v_lshlrev_b32_e32 v122, 16, v61
	v_and_b32_e32 v123, 0xffff0000, v61
	v_lshlrev_b32_e32 v124, 16, v62
	v_and_b32_e32 v125, 0xffff0000, v62
	v_lshlrev_b32_e32 v126, 16, v63
	v_and_b32_e32 v127, 0xffff0000, v63
	v_pk_fma_f32 v[20:21], v[112:113], v[120:121], v[20:21]
	v_pk_fma_f32 v[22:23], v[114:115], v[122:123], v[22:23]
	v_pk_fma_f32 v[24:25], v[116:117], v[124:125], v[24:25]
	v_pk_fma_f32 v[26:27], v[118:119], v[126:127], v[26:27]
	v_lshlrev_b32_e32 v112, 16, v64
	v_and_b32_e32 v113, 0xffff0000, v64
	v_lshlrev_b32_e32 v114, 16, v65
	v_and_b32_e32 v115, 0xffff0000, v65
	v_lshlrev_b32_e32 v116, 16, v66
	v_and_b32_e32 v117, 0xffff0000, v66
	v_lshlrev_b32_e32 v118, 16, v67
	v_and_b32_e32 v119, 0xffff0000, v67
	v_pk_mul_f32 v[112:113], v[88:89], v[112:113]
	v_pk_mul_f32 v[114:115], v[90:91], v[114:115]
	v_pk_mul_f32 v[116:117], v[92:93], v[116:117]
	v_pk_mul_f32 v[118:119], v[94:95], v[118:119]
	v_lshlrev_b32_e32 v120, 16, v68
	v_and_b32_e32 v121, 0xffff0000, v68
	v_lshlrev_b32_e32 v122, 16, v69
	v_and_b32_e32 v123, 0xffff0000, v69
	v_lshlrev_b32_e32 v124, 16, v70
	v_and_b32_e32 v125, 0xffff0000, v70
	v_lshlrev_b32_e32 v126, 16, v71
	v_and_b32_e32 v127, 0xffff0000, v71
	v_pk_fma_f32 v[20:21], v[112:113], v[120:121], v[20:21]
	v_pk_fma_f32 v[22:23], v[114:115], v[122:123], v[22:23]
	v_pk_fma_f32 v[24:25], v[116:117], v[124:125], v[24:25]
	v_pk_fma_f32 v[26:27], v[118:119], v[126:127], v[26:27]
	v_lshlrev_b32_e32 v112, 16, v72
	v_and_b32_e32 v113, 0xffff0000, v72
	v_lshlrev_b32_e32 v114, 16, v73
	v_and_b32_e32 v115, 0xffff0000, v73
	v_lshlrev_b32_e32 v116, 16, v74
	v_and_b32_e32 v117, 0xffff0000, v74
	v_lshlrev_b32_e32 v118, 16, v75
	v_and_b32_e32 v119, 0xffff0000, v75
	v_pk_mul_f32 v[112:113], v[100:101], v[112:113]
	v_pk_mul_f32 v[114:115], v[102:103], v[114:115]
	v_pk_mul_f32 v[116:117], v[104:105], v[116:117]
	v_pk_mul_f32 v[118:119], v[106:107], v[118:119]
	v_lshlrev_b32_e32 v120, 16, v76
	v_and_b32_e32 v121, 0xffff0000, v76
	v_lshlrev_b32_e32 v122, 16, v77
	v_and_b32_e32 v123, 0xffff0000, v77
	v_lshlrev_b32_e32 v124, 16, v78
	v_and_b32_e32 v125, 0xffff0000, v78
	v_lshlrev_b32_e32 v126, 16, v79
	v_and_b32_e32 v127, 0xffff0000, v79
	v_pk_fma_f32 v[20:21], v[112:113], v[120:121], v[20:21]
	v_pk_fma_f32 v[22:23], v[114:115], v[122:123], v[22:23]
	v_pk_fma_f32 v[24:25], v[116:117], v[124:125], v[24:25]
	v_pk_fma_f32 v[26:27], v[118:119], v[126:127], v[26:27]
	v_lshlrev_b32_e32 v112, 16, v108
	v_and_b32_e32 v113, 0xffff0000, v108
	v_lshlrev_b32_e32 v114, 16, v109
	v_and_b32_e32 v115, 0xffff0000, v109
	v_lshlrev_b32_e32 v116, 16, v110
	v_and_b32_e32 v117, 0xffff0000, v110
	v_lshlrev_b32_e32 v118, 16, v111
	v_and_b32_e32 v119, 0xffff0000, v111
	v_pk_mul_f32 v[20:21], v[20:21], v[112:113]
	v_pk_mul_f32 v[22:23], v[22:23], v[114:115]
	v_pk_mul_f32 v[24:25], v[24:25], v[116:117]
	v_pk_mul_f32 v[26:27], v[26:27], v[118:119]
	v_cvt_pk_bf16_f32 v112, v20, v21
	v_cvt_pk_bf16_f32 v113, v22, v23
	v_cvt_pk_bf16_f32 v114, v24, v25
	v_cvt_pk_bf16_f32 v115, v26, v27
	global_store_dwordx4 v[4:5], v[112:115], off
	s_add_i32 s95, s95, s94
	s_cmp_lt_i32 s95, s93
	s_cbranch_scc1 .Lcf1_loop
